# k8
# baseline (speedup 1.0000x reference)
; template <int EPI>
; __device__ __forceinline__ void gemm_phase(const GemmDesc d, u16* shm, unsigned sx, unsigned srank, unsigned snloc) {
;     ...
;         const int b = pn >> 4, s0 = (pn & 15) * 128;
;         const float sgn = (pm == 0) ? 1.f : -1.f;
;         float rs0[2], rs1[2];
; #pragma unroll
;         for (int n = 0; n < 2; ++n) { rs0[n] = lr[wc2 * 32 + n * 16 + fr2]; rs1[n] = sgn * lr[128 + wc2 * 32 + n * 16 + fr2]; }
;         u16* outp = d.outb + ((size_t)b * 1024 + z * 256) * 4096 + (size_t)pm * 2048 + s0 + wc2 * 32 + c4;
; #pragma unroll
;         for (int ai = 0; ai < 2; ++ai)
; #pragma unroll
;           for (int m = 0; m < 4; ++m) {
; #pragma unroll
;             for (int j = 0; j < 4; ++j) {
;               const float v0 = acc[ai][0][m][0][j] * rs0[0] + acc[ai][1][m][0][j] * rs1[0];
;               const float v1 = acc[ai][0][m][1][j] * rs0[1] + acc[ai][1][m][1][j] * rs1[1];
;               stg[(fq2 * 4 + j) * 36 + fr2] = v0; stg[(fq2 * 4 + j) * 36 + 16 + fr2] = v1;
;               if (pm == 0) {
;                 float a = (fr2 & 1) ? -(v0 + v1) : (v0 + v1);
;                 a += __shfl_xor(a, 1); a += __shfl_xor(a, 2); a += __shfl_xor(a, 4); a += __shfl_xor(a, 8);
;                 if (fr2 == 0) d.xs[((size_t)((pn & 15) * 4 + wc2)) * (NBATCH * DM) + (size_t)b * DM + z * 256 + ai * 128 + wr2 * 64 + m * 16 + fq2 * 4 + j] = a;
.LBB0_212:
	s_or_b64 exec, exec, s[4:5]
	v_ashrrev_i32_e32 v132, 6, v149
	s_movk_i32 s4, 0x900
	v_mul_lo_u32 v135, v132, s4
	s_lshl_b32 s4, s6, 8
	s_and_b32 s28, s4, 0x100
	s_lshl_b32 s4, s28, 2
	v_and_b32_e32 v153, 3, v132
	v_and_b32_e32 v134, 15, v149
	s_add_i32 s4, s4, 0
	s_add_i32 s4, s4, 0x20000
	v_lshlrev_b32_e32 v132, 7, v153
	v_lshlrev_b32_e32 v155, 2, v134
	v_add3_u32 v136, s4, v132, v155
	s_and_b32 s20, s85, 15
	ds_read2_b32 v[132:133], v136 offset0:128 offset1:144
	s_cmp_eq_u32 s84, 0
	s_cselect_b64 s[22:23], -1, 0
	s_ashr_i32 s18, s85, 4
	s_ashr_i32 s19, s18, 31
	s_lshl_b32 s4, s96, 8
	s_ashr_i32 s5, s4, 31
	s_lshl_b64 s[12:13], s[18:19], 12
	s_add_u32 s16, s1, s12
	s_waitcnt lgkmcnt(0)
	v_cndmask_b32_e64 v152, -v132, v132, s[22:23]
	v_lshrrev_b32_e32 v132, 2, v149
	s_addc_u32 s17, s57, s13
	s_lshl_b32 s21, s20, 17
	v_and_b32_e32 v156, 12, v132
	v_and_b32_e32 v132, 1, v149
	ds_read2_b32 v[136:137], v136 offset1:16
	v_cmp_eq_u32_e64 s[14:15], 0, v132
	v_ashrrev_i32_e32 v132, 2, v149
	v_lshl_or_b32 v176, v153, 15, s21
	v_add_u32_e32 v154, s83, v135
	v_cmp_eq_u32_e64 s[12:13], 0, v134
	v_and_b32_e32 v132, 0xffffffc0, v132
	v_lshl_add_u64 v[134:135], s[16:17], 0, v[176:177]
	v_cndmask_b32_e64 v151, -v133, v133, s[22:23]
	v_ashrrev_i32_e32 v133, 31, v132
	v_lshl_add_u64 v[134:135], s[4:5], 2, v[134:135]
	v_lshl_add_u64 v[134:135], v[132:133], 2, v[134:135]
	v_mul_f32_e32 v133, v116, v152
	v_mul_u32_u24_e32 v116, 36, v156
	v_lshlrev_b32_e32 v176, 2, v156
	v_mul_f32_e32 v112, v112, v151
	v_lshlrev_b32_e32 v116, 2, v116
	s_cmp_lg_u32 s84, 0
	v_lshl_add_u64 v[134:135], v[134:135], 0, v[176:177]
	s_waitcnt lgkmcnt(0)
	v_fmac_f32_e32 v133, v124, v136
	v_fmac_f32_e32 v112, v120, v137
	v_add3_u32 v120, v154, v155, v116
	v_add3_u32 v116, v154, v116, v155
	s_mov_b32 s31, 0x800000
	v_readlane_b32 s52, v239, 23
	ds_write_b32 v120, v133
	ds_write_b32 v116, v112 offset:64
	s_cbranch_scc1 .LBB0_216
	v_add_f32_e32 v112, v133, v112
	v_cndmask_b32_e64 v112, -v112, v112, s[14:15]
	s_nop 1
	v_add_f32_dpp v112, v112, v112 quad_perm:[1,0,3,2] row_mask:0xf bank_mask:0xf
	s_waitcnt lgkmcnt(0)
	s_nop 1
	v_add_f32_dpp v112, v112, v112 quad_perm:[2,3,0,1] row_mask:0xf bank_mask:0xf
	s_waitcnt lgkmcnt(0)
	s_nop 1
	v_add_f32_dpp v112, v112, v112 row_half_mirror row_mask:0xf bank_mask:0xf
	s_waitcnt lgkmcnt(0)
	s_nop 1
	v_add_f32_dpp v112, v112, v112 row_mirror row_mask:0xf bank_mask:0xf
	s_and_saveexec_b64 s[16:17], s[12:13]
	s_cbranch_execz .LBB0_215
	s_waitcnt lgkmcnt(0)
	global_store_dword v[134:135], v112, off

; template <int EPI>
; __device__ __forceinline__ void gemm_phase(const GemmDesc d, u16* shm, unsigned sx, unsigned srank, unsigned snloc) {
;     ...
;             for (int j = 0; j < 4; ++j) {
;               const float v0 = acc[ai][0][m][0][j] * rs0[0] + acc[ai][1][m][0][j] * rs1[0];
;               const float v1 = acc[ai][0][m][1][j] * rs0[1] + acc[ai][1][m][1][j] * rs1[1];
;               stg[(fq2 * 4 + j) * 36 + fr2] = v0; stg[(fq2 * 4 + j) * 36 + 16 + fr2] = v1;
;               if (pm == 0) {
;                 float a = (fr2 & 1) ? -(v0 + v1) : (v0 + v1);
;                 a += __shfl_xor(a, 1); a += __shfl_xor(a, 2); a += __shfl_xor(a, 4); a += __shfl_xor(a, 8);
;                 if (fr2 == 0) d.xs[((size_t)((pn & 15) * 4 + wc2)) * (NBATCH * DM) + (size_t)b * DM + z * 256 + ai * 128 + wr2 * 64 + m * 16 + fq2 * 4 + j] = a;
.LBB0_216:
	v_mul_f32_e32 v112, v117, v152
	v_mul_f32_e32 v113, v113, v151
	v_cndmask_b32_e64 v117, 0, 1, s[22:23]
	v_fmac_f32_e32 v112, v125, v136
	v_fmac_f32_e32 v113, v121, v137
	v_cmp_ne_u32_e64 s[16:17], 1, v117
	s_andn2_b64 vcc, exec, s[22:23]
	ds_write_b32 v120, v112 offset:144
	ds_write_b32 v116, v113 offset:208
	s_cbranch_vccnz .LBB0_220
	v_add_f32_e32 v112, v112, v113
	v_cndmask_b32_e64 v112, -v112, v112, s[14:15]
	s_nop 1
	v_add_f32_dpp v112, v112, v112 quad_perm:[1,0,3,2] row_mask:0xf bank_mask:0xf
	s_waitcnt lgkmcnt(0)
	s_nop 1
	v_add_f32_dpp v112, v112, v112 quad_perm:[2,3,0,1] row_mask:0xf bank_mask:0xf
	s_waitcnt lgkmcnt(0)
	s_nop 1
	v_add_f32_dpp v112, v112, v112 row_half_mirror row_mask:0xf bank_mask:0xf
	s_waitcnt lgkmcnt(0)
	s_nop 1
	v_add_f32_dpp v112, v112, v112 row_mirror row_mask:0xf bank_mask:0xf
	s_and_saveexec_b64 s[22:23], s[12:13]
	s_cbranch_execz .LBB0_219
	s_waitcnt lgkmcnt(0)
	global_store_dword v[134:135], v112, off offset:4

; template <int EPI>
; __device__ __forceinline__ void gemm_phase(const GemmDesc d, u16* shm, unsigned sx, unsigned srank, unsigned snloc) {
;     ...
;             for (int j = 0; j < 4; ++j) {
;               const float v0 = acc[ai][0][m][0][j] * rs0[0] + acc[ai][1][m][0][j] * rs1[0];
;               const float v1 = acc[ai][0][m][1][j] * rs0[1] + acc[ai][1][m][1][j] * rs1[1];
;               stg[(fq2 * 4 + j) * 36 + fr2] = v0; stg[(fq2 * 4 + j) * 36 + 16 + fr2] = v1;
;               if (pm == 0) {
;                 float a = (fr2 & 1) ? -(v0 + v1) : (v0 + v1);
;                 a += __shfl_xor(a, 1); a += __shfl_xor(a, 2); a += __shfl_xor(a, 4); a += __shfl_xor(a, 8);
;                 if (fr2 == 0) d.xs[((size_t)((pn & 15) * 4 + wc2)) * (NBATCH * DM) + (size_t)b * DM + z * 256 + ai * 128 + wr2 * 64 + m * 16 + fq2 * 4 + j] = a;
.LBB0_220:
	v_mul_f32_e32 v112, v118, v152
	s_waitcnt lgkmcnt(0)
	v_mul_f32_e32 v113, v114, v151
	v_fmac_f32_e32 v112, v126, v136
	v_fmac_f32_e32 v113, v122, v137
	s_and_b64 vcc, exec, s[16:17]
	ds_write_b32 v120, v112 offset:288
	ds_write_b32 v116, v113 offset:352
	s_cbranch_vccnz .LBB0_224
	v_add_f32_e32 v112, v112, v113
	v_cndmask_b32_e64 v112, -v112, v112, s[14:15]
	s_nop 1
	v_add_f32_dpp v112, v112, v112 quad_perm:[1,0,3,2] row_mask:0xf bank_mask:0xf
	s_waitcnt lgkmcnt(0)
	s_nop 1
	v_add_f32_dpp v112, v112, v112 quad_perm:[2,3,0,1] row_mask:0xf bank_mask:0xf
	s_waitcnt lgkmcnt(0)
	s_nop 1
	v_add_f32_dpp v112, v112, v112 row_half_mirror row_mask:0xf bank_mask:0xf
	s_waitcnt lgkmcnt(0)
	s_nop 1
	v_add_f32_dpp v112, v112, v112 row_mirror row_mask:0xf bank_mask:0xf
	s_and_saveexec_b64 s[22:23], s[12:13]
	s_cbranch_execz .LBB0_223
	s_waitcnt lgkmcnt(0)
	global_store_dword v[134:135], v112, off offset:8

; template <int EPI>
; __device__ __forceinline__ void gemm_phase(const GemmDesc d, u16* shm, unsigned sx, unsigned srank, unsigned snloc) {
;     ...
;             for (int j = 0; j < 4; ++j) {
;               const float v0 = acc[ai][0][m][0][j] * rs0[0] + acc[ai][1][m][0][j] * rs1[0];
;               const float v1 = acc[ai][0][m][1][j] * rs0[1] + acc[ai][1][m][1][j] * rs1[1];
;               stg[(fq2 * 4 + j) * 36 + fr2] = v0; stg[(fq2 * 4 + j) * 36 + 16 + fr2] = v1;
;               if (pm == 0) {
;                 float a = (fr2 & 1) ? -(v0 + v1) : (v0 + v1);
;                 a += __shfl_xor(a, 1); a += __shfl_xor(a, 2); a += __shfl_xor(a, 4); a += __shfl_xor(a, 8);
;                 if (fr2 == 0) d.xs[((size_t)((pn & 15) * 4 + wc2)) * (NBATCH * DM) + (size_t)b * DM + z * 256 + ai * 128 + wr2 * 64 + m * 16 + fq2 * 4 + j] = a;
.LBB0_224:
	v_mul_f32_e32 v112, v119, v152
	s_waitcnt lgkmcnt(0)
	v_mul_f32_e32 v113, v115, v151
	v_fmac_f32_e32 v112, v127, v136
	v_fmac_f32_e32 v113, v123, v137
	s_and_b64 vcc, exec, s[16:17]
	ds_write_b32 v120, v112 offset:432
	ds_write_b32 v116, v113 offset:496
	s_cbranch_vccnz .LBB0_228
	v_add_f32_e32 v112, v112, v113
	v_cndmask_b32_e64 v112, -v112, v112, s[14:15]
	s_nop 1
	v_add_f32_dpp v112, v112, v112 quad_perm:[1,0,3,2] row_mask:0xf bank_mask:0xf
	s_waitcnt lgkmcnt(0)
	s_nop 1
	v_add_f32_dpp v112, v112, v112 quad_perm:[2,3,0,1] row_mask:0xf bank_mask:0xf
	s_waitcnt lgkmcnt(0)
	s_nop 1
	v_add_f32_dpp v112, v112, v112 row_half_mirror row_mask:0xf bank_mask:0xf
	s_waitcnt lgkmcnt(0)
	s_nop 1
	v_add_f32_dpp v112, v112, v112 row_mirror row_mask:0xf bank_mask:0xf
	s_and_saveexec_b64 s[22:23], s[12:13]
	s_cbranch_execz .LBB0_227
	s_waitcnt lgkmcnt(0)
	global_store_dword v[134:135], v112, off offset:12

; __device__ __forceinline__ unsigned pack2(float lo, float hi) { unsigned r; asm volatile("v_cvt_pk_bf16_f32 %0, %1, %2" : "=v"(r) : "v"(lo), "v"(hi)); return r; }
; template <int EPI>
; __device__ __forceinline__ void gemm_phase(const GemmDesc d, u16* shm, unsigned sx, unsigned srank, unsigned snloc) {
;     ...
;             for (int j = 0; j < 4; ++j) {
;               const float v0 = acc[ai][0][m][0][j] * rs0[0] + acc[ai][1][m][0][j] * rs1[0];
;               const float v1 = acc[ai][0][m][1][j] * rs0[1] + acc[ai][1][m][1][j] * rs1[1];
;               stg[(fq2 * 4 + j) * 36 + fr2] = v0; stg[(fq2 * 4 + j) * 36 + 16 + fr2] = v1;
;               if (pm == 0) {
;                 float a = (fr2 & 1) ? -(v0 + v1) : (v0 + v1);
;                 a += __shfl_xor(a, 1); a += __shfl_xor(a, 2); a += __shfl_xor(a, 4); a += __shfl_xor(a, 8);
;                 if (fr2 == 0) d.xs[((size_t)((pn & 15) * 4 + wc2)) * (NBATCH * DM) + (size_t)b * DM + z * 256 + ai * 128 + wr2 * 64 + m * 16 + fq2 * 4 + j] = a;
;               }
;             }
; #pragma unroll
;             for (int i = 0; i < 2; ++i) {
;               const int row_l = i * 8 + rl;
;               f32x4 v = *(const f32x4*)&stg[row_l * 36 + c4];
;               u32x2 w = {pack2(v[0], v[1]), pack2(v[2], v[3])};
;               *(u32x2*)(outp + (size_t)(ai * 128 + wr2 * 64 + m * 16 + row_l) * 4096) = w;
;             }
.LBB0_228:
	s_lshl_b64 s[18:19], s[18:19], 10
	s_add_u32 s4, s18, s4
	s_addc_u32 s5, s19, s5
	s_lshl_b64 s[4:5], s[4:5], 13
	s_add_u32 s4, s24, s4
	s_addc_u32 s5, s25, s5
	s_lshl_b32 s18, s84, 12
	s_add_u32 s4, s4, s18
	s_addc_u32 s5, s5, 0
	s_lshl_b32 s18, s20, 8
	v_lshlrev_b32_e32 v112, 2, v149
	s_add_u32 s4, s4, s18
	v_and_b32_e32 v115, 28, v112
	s_addc_u32 s5, s5, 0
	v_lshlrev_b32_e32 v176, 6, v153
	v_bfe_u32 v114, v149, 3, 3
	s_waitcnt lgkmcnt(0)
	v_lshl_add_u64 v[112:113], s[4:5], 0, v[176:177]
	v_lshl_add_u32 v117, v115, 2, v154
	s_movk_i32 s4, 0x90
	v_mad_u32_u24 v121, v114, s4, v117
	ds_read_b128 v[122:125], v121
	s_waitcnt lgkmcnt(0)
	v_cvt_pk_bf16_f32 v118, v122, v123
	v_or_b32_e32 v122, v114, v132
	v_lshlrev_b32_e32 v176, 1, v115
	v_ashrrev_i32_e32 v123, 31, v122
	v_lshl_add_u64 v[112:113], v[112:113], 0, v[176:177]
	v_lshlrev_b64 v[122:123], 13, v[122:123]
	v_lshl_add_u64 v[122:123], v[112:113], 0, v[122:123]
	v_cvt_pk_bf16_f32 v119, v124, v125
	global_store_dwordx2 v[122:123], v[118:119], off
	v_or_b32_e32 v115, 8, v114
	ds_read_b128 v[122:125], v121 offset:1152
	s_waitcnt lgkmcnt(0)
	v_cvt_pk_bf16_f32 v118, v122, v123
	v_or_b32_e32 v122, v115, v132
	v_ashrrev_i32_e32 v123, 31, v122
	v_lshlrev_b64 v[122:123], 13, v[122:123]
	v_mul_f32_e32 v100, v100, v152
	v_mul_f32_e32 v96, v96, v151
	v_lshl_add_u64 v[122:123], v[112:113], 0, v[122:123]
	v_fmac_f32_e32 v100, v108, v136
	v_fmac_f32_e32 v96, v104, v137
	s_and_b64 vcc, exec, s[16:17]
	v_cvt_pk_bf16_f32 v119, v124, v125
	global_store_dwordx2 v[122:123], v[118:119], off
	ds_write_b32 v120, v100
	ds_write_b32 v116, v96 offset:64
	s_cbranch_vccnz .LBB0_232
	v_add_f32_e32 v96, v100, v96
	v_cndmask_b32_e64 v96, -v96, v96, s[14:15]
	s_nop 1
	v_add_f32_dpp v96, v96, v96 quad_perm:[1,0,3,2] row_mask:0xf bank_mask:0xf
	s_waitcnt lgkmcnt(0)
	s_nop 1
	v_add_f32_dpp v96, v96, v96 quad_perm:[2,3,0,1] row_mask:0xf bank_mask:0xf
	s_waitcnt lgkmcnt(0)
	s_nop 1
	v_add_f32_dpp v96, v96, v96 row_half_mirror row_mask:0xf bank_mask:0xf
	s_waitcnt lgkmcnt(0)
	s_nop 1
	v_add_f32_dpp v96, v96, v96 row_mirror row_mask:0xf bank_mask:0xf
	s_and_saveexec_b64 s[4:5], s[12:13]
	s_cbranch_execz .LBB0_231
	s_waitcnt lgkmcnt(0)
	global_store_dword v[134:135], v96, off offset:64

; template <int EPI>
; __device__ __forceinline__ void gemm_phase(const GemmDesc d, u16* shm, unsigned sx, unsigned srank, unsigned snloc) {
;     ...
;             for (int j = 0; j < 4; ++j) {
;               const float v0 = acc[ai][0][m][0][j] * rs0[0] + acc[ai][1][m][0][j] * rs1[0];
;               const float v1 = acc[ai][0][m][1][j] * rs0[1] + acc[ai][1][m][1][j] * rs1[1];
;               stg[(fq2 * 4 + j) * 36 + fr2] = v0; stg[(fq2 * 4 + j) * 36 + 16 + fr2] = v1;
;               if (pm == 0) {
;                 float a = (fr2 & 1) ? -(v0 + v1) : (v0 + v1);
;                 a += __shfl_xor(a, 1); a += __shfl_xor(a, 2); a += __shfl_xor(a, 4); a += __shfl_xor(a, 8);
;                 if (fr2 == 0) d.xs[((size_t)((pn & 15) * 4 + wc2)) * (NBATCH * DM) + (size_t)b * DM + z * 256 + ai * 128 + wr2 * 64 + m * 16 + fq2 * 4 + j] = a;
.LBB0_232:
	v_mul_f32_e32 v96, v101, v152
	v_mul_f32_e32 v97, v97, v151
	v_fmac_f32_e32 v96, v109, v136
	v_fmac_f32_e32 v97, v105, v137
	s_and_b64 vcc, exec, s[16:17]
	ds_write_b32 v120, v96 offset:144
	ds_write_b32 v116, v97 offset:208
	s_cbranch_vccnz .LBB0_236
	s_waitcnt lgkmcnt(2)
	v_add_f32_e32 v96, v96, v97
	v_cndmask_b32_e64 v96, -v96, v96, s[14:15]
	s_nop 1
	v_add_f32_dpp v96, v96, v96 quad_perm:[1,0,3,2] row_mask:0xf bank_mask:0xf
	s_waitcnt lgkmcnt(0)
	s_nop 1
	v_add_f32_dpp v96, v96, v96 quad_perm:[2,3,0,1] row_mask:0xf bank_mask:0xf
	s_waitcnt lgkmcnt(0)
	s_nop 1
	v_add_f32_dpp v96, v96, v96 row_half_mirror row_mask:0xf bank_mask:0xf
	s_waitcnt lgkmcnt(0)
	s_nop 1
	v_add_f32_dpp v96, v96, v96 row_mirror row_mask:0xf bank_mask:0xf
	s_and_saveexec_b64 s[4:5], s[12:13]
	s_cbranch_execz .LBB0_235
	s_waitcnt lgkmcnt(0)
	global_store_dword v[134:135], v96, off offset:68

; template <int EPI>
; __device__ __forceinline__ void gemm_phase(const GemmDesc d, u16* shm, unsigned sx, unsigned srank, unsigned snloc) {
;     ...
;             for (int j = 0; j < 4; ++j) {
;               const float v0 = acc[ai][0][m][0][j] * rs0[0] + acc[ai][1][m][0][j] * rs1[0];
;               const float v1 = acc[ai][0][m][1][j] * rs0[1] + acc[ai][1][m][1][j] * rs1[1];
;               stg[(fq2 * 4 + j) * 36 + fr2] = v0; stg[(fq2 * 4 + j) * 36 + 16 + fr2] = v1;
;               if (pm == 0) {
;                 float a = (fr2 & 1) ? -(v0 + v1) : (v0 + v1);
;                 a += __shfl_xor(a, 1); a += __shfl_xor(a, 2); a += __shfl_xor(a, 4); a += __shfl_xor(a, 8);
;                 if (fr2 == 0) d.xs[((size_t)((pn & 15) * 4 + wc2)) * (NBATCH * DM) + (size_t)b * DM + z * 256 + ai * 128 + wr2 * 64 + m * 16 + fq2 * 4 + j] = a;
.LBB0_236:
	v_mul_f32_e32 v96, v102, v152
	s_waitcnt lgkmcnt(0)
	v_mul_f32_e32 v97, v98, v151
	v_fmac_f32_e32 v96, v110, v136
	v_fmac_f32_e32 v97, v106, v137
	s_and_b64 vcc, exec, s[16:17]
	ds_write_b32 v120, v96 offset:288
	ds_write_b32 v116, v97 offset:352
	s_cbranch_vccnz .LBB0_240
	v_add_f32_e32 v96, v96, v97
	v_cndmask_b32_e64 v96, -v96, v96, s[14:15]
	s_nop 1
	v_add_f32_dpp v96, v96, v96 quad_perm:[1,0,3,2] row_mask:0xf bank_mask:0xf
	s_waitcnt lgkmcnt(0)
	s_nop 1
	v_add_f32_dpp v96, v96, v96 quad_perm:[2,3,0,1] row_mask:0xf bank_mask:0xf
	s_waitcnt lgkmcnt(0)
	s_nop 1
	v_add_f32_dpp v96, v96, v96 row_half_mirror row_mask:0xf bank_mask:0xf
	s_waitcnt lgkmcnt(0)
	s_nop 1
	v_add_f32_dpp v96, v96, v96 row_mirror row_mask:0xf bank_mask:0xf
	s_and_saveexec_b64 s[4:5], s[12:13]
	s_cbranch_execz .LBB0_239
	s_waitcnt lgkmcnt(0)
	global_store_dword v[134:135], v96, off offset:72

; template <int EPI>
; __device__ __forceinline__ void gemm_phase(const GemmDesc d, u16* shm, unsigned sx, unsigned srank, unsigned snloc) {
;     ...
;             for (int j = 0; j < 4; ++j) {
;               const float v0 = acc[ai][0][m][0][j] * rs0[0] + acc[ai][1][m][0][j] * rs1[0];
;               const float v1 = acc[ai][0][m][1][j] * rs0[1] + acc[ai][1][m][1][j] * rs1[1];
;               stg[(fq2 * 4 + j) * 36 + fr2] = v0; stg[(fq2 * 4 + j) * 36 + 16 + fr2] = v1;
;               if (pm == 0) {
;                 float a = (fr2 & 1) ? -(v0 + v1) : (v0 + v1);
;                 a += __shfl_xor(a, 1); a += __shfl_xor(a, 2); a += __shfl_xor(a, 4); a += __shfl_xor(a, 8);
;                 if (fr2 == 0) d.xs[((size_t)((pn & 15) * 4 + wc2)) * (NBATCH * DM) + (size_t)b * DM + z * 256 + ai * 128 + wr2 * 64 + m * 16 + fq2 * 4 + j] = a;
.LBB0_240:
	v_mul_f32_e32 v96, v103, v152
	s_waitcnt lgkmcnt(0)
	v_mul_f32_e32 v97, v99, v151
	v_fmac_f32_e32 v96, v111, v136
	v_fmac_f32_e32 v97, v107, v137
	s_and_b64 vcc, exec, s[16:17]
	ds_write_b32 v120, v96 offset:432
	ds_write_b32 v116, v97 offset:496
	s_cbranch_vccnz .LBB0_244
	v_add_f32_e32 v96, v96, v97
	v_cndmask_b32_e64 v96, -v96, v96, s[14:15]
	s_nop 1
	v_add_f32_dpp v96, v96, v96 quad_perm:[1,0,3,2] row_mask:0xf bank_mask:0xf
	s_waitcnt lgkmcnt(0)
	s_nop 1
	v_add_f32_dpp v96, v96, v96 quad_perm:[2,3,0,1] row_mask:0xf bank_mask:0xf
	s_waitcnt lgkmcnt(0)
	s_nop 1
	v_add_f32_dpp v96, v96, v96 row_half_mirror row_mask:0xf bank_mask:0xf
	s_waitcnt lgkmcnt(0)
	s_nop 1
	v_add_f32_dpp v96, v96, v96 row_mirror row_mask:0xf bank_mask:0xf
	s_and_saveexec_b64 s[4:5], s[12:13]
	s_cbranch_execz .LBB0_243
	s_waitcnt lgkmcnt(0)
	global_store_dword v[134:135], v96, off offset:76

; __device__ __forceinline__ unsigned pack2(float lo, float hi) { unsigned r; asm volatile("v_cvt_pk_bf16_f32 %0, %1, %2" : "=v"(r) : "v"(lo), "v"(hi)); return r; }
; template <int EPI>
; __device__ __forceinline__ void gemm_phase(const GemmDesc d, u16* shm, unsigned sx, unsigned srank, unsigned snloc) {
;     ...
;             for (int j = 0; j < 4; ++j) {
;               const float v0 = acc[ai][0][m][0][j] * rs0[0] + acc[ai][1][m][0][j] * rs1[0];
;               const float v1 = acc[ai][0][m][1][j] * rs0[1] + acc[ai][1][m][1][j] * rs1[1];
;               stg[(fq2 * 4 + j) * 36 + fr2] = v0; stg[(fq2 * 4 + j) * 36 + 16 + fr2] = v1;
;               if (pm == 0) {
;                 float a = (fr2 & 1) ? -(v0 + v1) : (v0 + v1);
;                 a += __shfl_xor(a, 1); a += __shfl_xor(a, 2); a += __shfl_xor(a, 4); a += __shfl_xor(a, 8);
;                 if (fr2 == 0) d.xs[((size_t)((pn & 15) * 4 + wc2)) * (NBATCH * DM) + (size_t)b * DM + z * 256 + ai * 128 + wr2 * 64 + m * 16 + fq2 * 4 + j] = a;
;               }
;             }
; #pragma unroll
;             for (int i = 0; i < 2; ++i) {
;               const int row_l = i * 8 + rl;
;               f32x4 v = *(const f32x4*)&stg[row_l * 36 + c4];
;               u32x2 w = {pack2(v[0], v[1]), pack2(v[2], v[3])};
;               *(u32x2*)(outp + (size_t)(ai * 128 + wr2 * 64 + m * 16 + row_l) * 4096) = w;
;             }
.LBB0_244:
	v_mul_u32_u24_e32 v96, 0x90, v114
	v_add_u32_e32 v96, v117, v96
	s_waitcnt lgkmcnt(0)
	v_or_b32_e32 v97, 16, v132
	ds_read_b128 v[98:101], v96
	s_waitcnt lgkmcnt(0)
	v_cvt_pk_bf16_f32 v98, v98, v99
	v_cvt_pk_bf16_f32 v99, v100, v101
	v_or_b32_e32 v100, v97, v114
	v_ashrrev_i32_e32 v101, 31, v100
	v_lshlrev_b64 v[100:101], 13, v[100:101]
	v_lshl_add_u64 v[100:101], v[112:113], 0, v[100:101]
	global_store_dwordx2 v[100:101], v[98:99], off
	ds_read_b128 v[98:101], v96 offset:1152
	s_waitcnt lgkmcnt(0)
	v_cvt_pk_bf16_f32 v98, v98, v99
	v_cvt_pk_bf16_f32 v99, v100, v101
	v_or_b32_e32 v100, v115, v97
	v_ashrrev_i32_e32 v101, 31, v100
	v_lshlrev_b64 v[100:101], 13, v[100:101]
	v_mul_f32_e32 v84, v84, v152
	v_mul_f32_e32 v80, v80, v151
	v_lshl_add_u64 v[100:101], v[112:113], 0, v[100:101]
	v_fmac_f32_e32 v84, v92, v136
	v_fmac_f32_e32 v80, v88, v137
	s_and_b64 vcc, exec, s[16:17]
	global_store_dwordx2 v[100:101], v[98:99], off
	ds_write_b32 v120, v84
	ds_write_b32 v116, v80 offset:64
	s_cbranch_vccnz .LBB0_248
	v_add_f32_e32 v80, v84, v80
	v_cndmask_b32_e64 v80, -v80, v80, s[14:15]
	s_nop 1
	v_add_f32_dpp v80, v80, v80 quad_perm:[1,0,3,2] row_mask:0xf bank_mask:0xf
	s_waitcnt lgkmcnt(0)
	s_nop 1
	v_add_f32_dpp v80, v80, v80 quad_perm:[2,3,0,1] row_mask:0xf bank_mask:0xf
	s_waitcnt lgkmcnt(0)
	s_nop 1
	v_add_f32_dpp v80, v80, v80 row_half_mirror row_mask:0xf bank_mask:0xf
	s_waitcnt lgkmcnt(0)
	s_nop 1
	v_add_f32_dpp v80, v80, v80 row_mirror row_mask:0xf bank_mask:0xf
	s_and_saveexec_b64 s[4:5], s[12:13]
	s_cbranch_execz .LBB0_247
	s_waitcnt lgkmcnt(0)
	global_store_dword v[134:135], v80, off offset:128

; template <int EPI>
; __device__ __forceinline__ void gemm_phase(const GemmDesc d, u16* shm, unsigned sx, unsigned srank, unsigned snloc) {
;     ...
;             for (int j = 0; j < 4; ++j) {
;               const float v0 = acc[ai][0][m][0][j] * rs0[0] + acc[ai][1][m][0][j] * rs1[0];
;               const float v1 = acc[ai][0][m][1][j] * rs0[1] + acc[ai][1][m][1][j] * rs1[1];
;               stg[(fq2 * 4 + j) * 36 + fr2] = v0; stg[(fq2 * 4 + j) * 36 + 16 + fr2] = v1;
;               if (pm == 0) {
;                 float a = (fr2 & 1) ? -(v0 + v1) : (v0 + v1);
;                 a += __shfl_xor(a, 1); a += __shfl_xor(a, 2); a += __shfl_xor(a, 4); a += __shfl_xor(a, 8);
;                 if (fr2 == 0) d.xs[((size_t)((pn & 15) * 4 + wc2)) * (NBATCH * DM) + (size_t)b * DM + z * 256 + ai * 128 + wr2 * 64 + m * 16 + fq2 * 4 + j] = a;
.LBB0_248:
	v_mul_f32_e32 v80, v85, v152
	v_mul_f32_e32 v81, v81, v151
	v_fmac_f32_e32 v80, v93, v136
	v_fmac_f32_e32 v81, v89, v137
	s_and_b64 vcc, exec, s[16:17]
	ds_write_b32 v120, v80 offset:144
	ds_write_b32 v116, v81 offset:208
	s_cbranch_vccnz .LBB0_252
	s_waitcnt lgkmcnt(2)
	v_add_f32_e32 v80, v80, v81
	v_cndmask_b32_e64 v80, -v80, v80, s[14:15]
	s_nop 1
	v_add_f32_dpp v80, v80, v80 quad_perm:[1,0,3,2] row_mask:0xf bank_mask:0xf
	s_waitcnt lgkmcnt(0)
	s_nop 1
	v_add_f32_dpp v80, v80, v80 quad_perm:[2,3,0,1] row_mask:0xf bank_mask:0xf
	s_waitcnt lgkmcnt(0)
	s_nop 1
	v_add_f32_dpp v80, v80, v80 row_half_mirror row_mask:0xf bank_mask:0xf
	s_waitcnt lgkmcnt(0)
	s_nop 1
	v_add_f32_dpp v80, v80, v80 row_mirror row_mask:0xf bank_mask:0xf
	s_and_saveexec_b64 s[4:5], s[12:13]
	s_cbranch_execz .LBB0_251
	s_waitcnt lgkmcnt(0)
	global_store_dword v[134:135], v80, off offset:132

; template <int EPI>
; __device__ __forceinline__ void gemm_phase(const GemmDesc d, u16* shm, unsigned sx, unsigned srank, unsigned snloc) {
;     ...
;             for (int j = 0; j < 4; ++j) {
;               const float v0 = acc[ai][0][m][0][j] * rs0[0] + acc[ai][1][m][0][j] * rs1[0];
;               const float v1 = acc[ai][0][m][1][j] * rs0[1] + acc[ai][1][m][1][j] * rs1[1];
;               stg[(fq2 * 4 + j) * 36 + fr2] = v0; stg[(fq2 * 4 + j) * 36 + 16 + fr2] = v1;
;               if (pm == 0) {
;                 float a = (fr2 & 1) ? -(v0 + v1) : (v0 + v1);
;                 a += __shfl_xor(a, 1); a += __shfl_xor(a, 2); a += __shfl_xor(a, 4); a += __shfl_xor(a, 8);
;                 if (fr2 == 0) d.xs[((size_t)((pn & 15) * 4 + wc2)) * (NBATCH * DM) + (size_t)b * DM + z * 256 + ai * 128 + wr2 * 64 + m * 16 + fq2 * 4 + j] = a;
.LBB0_252:
	v_mul_f32_e32 v80, v86, v152
	s_waitcnt lgkmcnt(0)
	v_mul_f32_e32 v81, v82, v151
	v_fmac_f32_e32 v80, v94, v136
	v_fmac_f32_e32 v81, v90, v137
	s_and_b64 vcc, exec, s[16:17]
	ds_write_b32 v120, v80 offset:288
	ds_write_b32 v116, v81 offset:352
	s_cbranch_vccnz .LBB0_256
	v_add_f32_e32 v80, v80, v81
	v_cndmask_b32_e64 v80, -v80, v80, s[14:15]
	s_nop 1
	v_add_f32_dpp v80, v80, v80 quad_perm:[1,0,3,2] row_mask:0xf bank_mask:0xf
	s_waitcnt lgkmcnt(0)
	s_nop 1
	v_add_f32_dpp v80, v80, v80 quad_perm:[2,3,0,1] row_mask:0xf bank_mask:0xf
	s_waitcnt lgkmcnt(0)
	s_nop 1
	v_add_f32_dpp v80, v80, v80 row_half_mirror row_mask:0xf bank_mask:0xf
	s_waitcnt lgkmcnt(0)
	s_nop 1
	v_add_f32_dpp v80, v80, v80 row_mirror row_mask:0xf bank_mask:0xf
	s_and_saveexec_b64 s[4:5], s[12:13]
	s_cbranch_execz .LBB0_255
	s_waitcnt lgkmcnt(0)
	global_store_dword v[134:135], v80, off offset:136

; template <int EPI>
; __device__ __forceinline__ void gemm_phase(const GemmDesc d, u16* shm, unsigned sx, unsigned srank, unsigned snloc) {
;     ...
;             for (int j = 0; j < 4; ++j) {
;               const float v0 = acc[ai][0][m][0][j] * rs0[0] + acc[ai][1][m][0][j] * rs1[0];
;               const float v1 = acc[ai][0][m][1][j] * rs0[1] + acc[ai][1][m][1][j] * rs1[1];
;               stg[(fq2 * 4 + j) * 36 + fr2] = v0; stg[(fq2 * 4 + j) * 36 + 16 + fr2] = v1;
;               if (pm == 0) {
;                 float a = (fr2 & 1) ? -(v0 + v1) : (v0 + v1);
;                 a += __shfl_xor(a, 1); a += __shfl_xor(a, 2); a += __shfl_xor(a, 4); a += __shfl_xor(a, 8);
;                 if (fr2 == 0) d.xs[((size_t)((pn & 15) * 4 + wc2)) * (NBATCH * DM) + (size_t)b * DM + z * 256 + ai * 128 + wr2 * 64 + m * 16 + fq2 * 4 + j] = a;
.LBB0_256:
	v_mul_f32_e32 v80, v87, v152
	s_waitcnt lgkmcnt(0)
	v_mul_f32_e32 v81, v83, v151
	v_fmac_f32_e32 v80, v95, v136
	v_fmac_f32_e32 v81, v91, v137
	s_and_b64 vcc, exec, s[16:17]
	ds_write_b32 v120, v80 offset:432
	ds_write_b32 v116, v81 offset:496
	s_cbranch_vccnz .LBB0_260
	v_add_f32_e32 v80, v80, v81
	v_cndmask_b32_e64 v80, -v80, v80, s[14:15]
	s_nop 1
	v_add_f32_dpp v80, v80, v80 quad_perm:[1,0,3,2] row_mask:0xf bank_mask:0xf
	s_waitcnt lgkmcnt(0)
	s_nop 1
	v_add_f32_dpp v80, v80, v80 quad_perm:[2,3,0,1] row_mask:0xf bank_mask:0xf
	s_waitcnt lgkmcnt(0)
	s_nop 1
	v_add_f32_dpp v80, v80, v80 row_half_mirror row_mask:0xf bank_mask:0xf
	s_waitcnt lgkmcnt(0)
	s_nop 1
	v_add_f32_dpp v80, v80, v80 row_mirror row_mask:0xf bank_mask:0xf
	s_and_saveexec_b64 s[4:5], s[12:13]
	s_cbranch_execz .LBB0_259
	s_waitcnt lgkmcnt(0)
	global_store_dword v[134:135], v80, off offset:140

; __device__ __forceinline__ unsigned pack2(float lo, float hi) { unsigned r; asm volatile("v_cvt_pk_bf16_f32 %0, %1, %2" : "=v"(r) : "v"(lo), "v"(hi)); return r; }
; template <int EPI>
; __device__ __forceinline__ void gemm_phase(const GemmDesc d, u16* shm, unsigned sx, unsigned srank, unsigned snloc) {
;     ...
;             for (int j = 0; j < 4; ++j) {
;               const float v0 = acc[ai][0][m][0][j] * rs0[0] + acc[ai][1][m][0][j] * rs1[0];
;               const float v1 = acc[ai][0][m][1][j] * rs0[1] + acc[ai][1][m][1][j] * rs1[1];
;               stg[(fq2 * 4 + j) * 36 + fr2] = v0; stg[(fq2 * 4 + j) * 36 + 16 + fr2] = v1;
;               if (pm == 0) {
;                 float a = (fr2 & 1) ? -(v0 + v1) : (v0 + v1);
;                 a += __shfl_xor(a, 1); a += __shfl_xor(a, 2); a += __shfl_xor(a, 4); a += __shfl_xor(a, 8);
;                 if (fr2 == 0) d.xs[((size_t)((pn & 15) * 4 + wc2)) * (NBATCH * DM) + (size_t)b * DM + z * 256 + ai * 128 + wr2 * 64 + m * 16 + fq2 * 4 + j] = a;
;               }
;             }
; #pragma unroll
;             for (int i = 0; i < 2; ++i) {
;               const int row_l = i * 8 + rl;
;               f32x4 v = *(const f32x4*)&stg[row_l * 36 + c4];
;               u32x2 w = {pack2(v[0], v[1]), pack2(v[2], v[3])};
;               *(u32x2*)(outp + (size_t)(ai * 128 + wr2 * 64 + m * 16 + row_l) * 4096) = w;
;             }
.LBB0_260:
	v_or_b32_e32 v84, 32, v132
	s_waitcnt lgkmcnt(0)
	ds_read_b128 v[80:83], v96
	s_waitcnt lgkmcnt(0)
	v_cvt_pk_bf16_f32 v80, v80, v81
	v_cvt_pk_bf16_f32 v81, v82, v83
	v_or_b32_e32 v82, v84, v114
	v_ashrrev_i32_e32 v83, 31, v82
	v_lshlrev_b64 v[82:83], 13, v[82:83]
	v_lshl_add_u64 v[82:83], v[112:113], 0, v[82:83]
	global_store_dwordx2 v[82:83], v[80:81], off
	ds_read_b128 v[80:83], v96 offset:1152
	s_waitcnt lgkmcnt(0)
	v_cvt_pk_bf16_f32 v80, v80, v81
	v_cvt_pk_bf16_f32 v81, v82, v83
	v_or_b32_e32 v82, v115, v84
	v_ashrrev_i32_e32 v83, 31, v82
	v_lshlrev_b64 v[82:83], 13, v[82:83]
	v_mul_f32_e32 v68, v68, v152
	v_mul_f32_e32 v64, v64, v151
	v_lshl_add_u64 v[82:83], v[112:113], 0, v[82:83]
	v_fmac_f32_e32 v68, v76, v136
	v_fmac_f32_e32 v64, v72, v137
	s_and_b64 vcc, exec, s[16:17]
	global_store_dwordx2 v[82:83], v[80:81], off
	ds_write_b32 v120, v68
	ds_write_b32 v116, v64 offset:64
	s_cbranch_vccnz .LBB0_264
	v_add_f32_e32 v64, v68, v64
	v_cndmask_b32_e64 v64, -v64, v64, s[14:15]
	s_nop 1
	v_add_f32_dpp v64, v64, v64 quad_perm:[1,0,3,2] row_mask:0xf bank_mask:0xf
	s_waitcnt lgkmcnt(0)
	s_nop 1
	v_add_f32_dpp v64, v64, v64 quad_perm:[2,3,0,1] row_mask:0xf bank_mask:0xf
	s_waitcnt lgkmcnt(0)
	s_nop 1
	v_add_f32_dpp v64, v64, v64 row_half_mirror row_mask:0xf bank_mask:0xf
	s_waitcnt lgkmcnt(0)
	s_nop 1
	v_add_f32_dpp v64, v64, v64 row_mirror row_mask:0xf bank_mask:0xf
	s_and_saveexec_b64 s[4:5], s[12:13]
	s_cbranch_execz .LBB0_263
	s_waitcnt lgkmcnt(0)
	global_store_dword v[134:135], v64, off offset:192

; template <int EPI>
; __device__ __forceinline__ void gemm_phase(const GemmDesc d, u16* shm, unsigned sx, unsigned srank, unsigned snloc) {
;     ...
;             for (int j = 0; j < 4; ++j) {
;               const float v0 = acc[ai][0][m][0][j] * rs0[0] + acc[ai][1][m][0][j] * rs1[0];
;               const float v1 = acc[ai][0][m][1][j] * rs0[1] + acc[ai][1][m][1][j] * rs1[1];
;               stg[(fq2 * 4 + j) * 36 + fr2] = v0; stg[(fq2 * 4 + j) * 36 + 16 + fr2] = v1;
;               if (pm == 0) {
;                 float a = (fr2 & 1) ? -(v0 + v1) : (v0 + v1);
;                 a += __shfl_xor(a, 1); a += __shfl_xor(a, 2); a += __shfl_xor(a, 4); a += __shfl_xor(a, 8);
;                 if (fr2 == 0) d.xs[((size_t)((pn & 15) * 4 + wc2)) * (NBATCH * DM) + (size_t)b * DM + z * 256 + ai * 128 + wr2 * 64 + m * 16 + fq2 * 4 + j] = a;
.LBB0_264:
	v_mul_f32_e32 v64, v69, v152
	v_mul_f32_e32 v65, v65, v151
	v_fmac_f32_e32 v64, v77, v136
	v_fmac_f32_e32 v65, v73, v137
	s_and_b64 vcc, exec, s[16:17]
	ds_write_b32 v120, v64 offset:144
	ds_write_b32 v116, v65 offset:208
	s_cbranch_vccnz .LBB0_268
	s_waitcnt lgkmcnt(2)
	v_add_f32_e32 v64, v64, v65
	v_cndmask_b32_e64 v64, -v64, v64, s[14:15]
	s_nop 1
	v_add_f32_dpp v64, v64, v64 quad_perm:[1,0,3,2] row_mask:0xf bank_mask:0xf
	s_waitcnt lgkmcnt(0)
	s_nop 1
	v_add_f32_dpp v64, v64, v64 quad_perm:[2,3,0,1] row_mask:0xf bank_mask:0xf
	s_waitcnt lgkmcnt(0)
	s_nop 1
	v_add_f32_dpp v64, v64, v64 row_half_mirror row_mask:0xf bank_mask:0xf
	s_waitcnt lgkmcnt(0)
	s_nop 1
	v_add_f32_dpp v64, v64, v64 row_mirror row_mask:0xf bank_mask:0xf
	s_and_saveexec_b64 s[4:5], s[12:13]
	s_cbranch_execz .LBB0_267
	s_waitcnt lgkmcnt(0)
	global_store_dword v[134:135], v64, off offset:196

; template <int EPI>
; __device__ __forceinline__ void gemm_phase(const GemmDesc d, u16* shm, unsigned sx, unsigned srank, unsigned snloc) {
;     ...
;             for (int j = 0; j < 4; ++j) {
;               const float v0 = acc[ai][0][m][0][j] * rs0[0] + acc[ai][1][m][0][j] * rs1[0];
;               const float v1 = acc[ai][0][m][1][j] * rs0[1] + acc[ai][1][m][1][j] * rs1[1];
;               stg[(fq2 * 4 + j) * 36 + fr2] = v0; stg[(fq2 * 4 + j) * 36 + 16 + fr2] = v1;
;               if (pm == 0) {
;                 float a = (fr2 & 1) ? -(v0 + v1) : (v0 + v1);
;                 a += __shfl_xor(a, 1); a += __shfl_xor(a, 2); a += __shfl_xor(a, 4); a += __shfl_xor(a, 8);
;                 if (fr2 == 0) d.xs[((size_t)((pn & 15) * 4 + wc2)) * (NBATCH * DM) + (size_t)b * DM + z * 256 + ai * 128 + wr2 * 64 + m * 16 + fq2 * 4 + j] = a;
.LBB0_268:
	v_mul_f32_e32 v64, v70, v152
	s_waitcnt lgkmcnt(0)
	v_mul_f32_e32 v65, v66, v151
	v_fmac_f32_e32 v64, v78, v136
	v_fmac_f32_e32 v65, v74, v137
	s_and_b64 vcc, exec, s[16:17]
	ds_write_b32 v120, v64 offset:288
	ds_write_b32 v116, v65 offset:352
	s_cbranch_vccnz .LBB0_272
	v_add_f32_e32 v64, v64, v65
	v_cndmask_b32_e64 v64, -v64, v64, s[14:15]
	s_nop 1
	v_add_f32_dpp v64, v64, v64 quad_perm:[1,0,3,2] row_mask:0xf bank_mask:0xf
	s_waitcnt lgkmcnt(0)
	s_nop 1
	v_add_f32_dpp v64, v64, v64 quad_perm:[2,3,0,1] row_mask:0xf bank_mask:0xf
	s_waitcnt lgkmcnt(0)
	s_nop 1
	v_add_f32_dpp v64, v64, v64 row_half_mirror row_mask:0xf bank_mask:0xf
	s_waitcnt lgkmcnt(0)
	s_nop 1
	v_add_f32_dpp v64, v64, v64 row_mirror row_mask:0xf bank_mask:0xf
	s_and_saveexec_b64 s[4:5], s[12:13]
	s_cbranch_execz .LBB0_271
	s_waitcnt lgkmcnt(0)
	global_store_dword v[134:135], v64, off offset:200

; template <int EPI>
; __device__ __forceinline__ void gemm_phase(const GemmDesc d, u16* shm, unsigned sx, unsigned srank, unsigned snloc) {
;     ...
;             for (int j = 0; j < 4; ++j) {
;               const float v0 = acc[ai][0][m][0][j] * rs0[0] + acc[ai][1][m][0][j] * rs1[0];
;               const float v1 = acc[ai][0][m][1][j] * rs0[1] + acc[ai][1][m][1][j] * rs1[1];
;               stg[(fq2 * 4 + j) * 36 + fr2] = v0; stg[(fq2 * 4 + j) * 36 + 16 + fr2] = v1;
;               if (pm == 0) {
;                 float a = (fr2 & 1) ? -(v0 + v1) : (v0 + v1);
;                 a += __shfl_xor(a, 1); a += __shfl_xor(a, 2); a += __shfl_xor(a, 4); a += __shfl_xor(a, 8);
;                 if (fr2 == 0) d.xs[((size_t)((pn & 15) * 4 + wc2)) * (NBATCH * DM) + (size_t)b * DM + z * 256 + ai * 128 + wr2 * 64 + m * 16 + fq2 * 4 + j] = a;
.LBB0_272:
	v_mul_f32_e32 v64, v71, v152
	s_waitcnt lgkmcnt(0)
	v_mul_f32_e32 v65, v67, v151
	v_fmac_f32_e32 v64, v79, v136
	v_fmac_f32_e32 v65, v75, v137
	s_and_b64 vcc, exec, s[16:17]
	ds_write_b32 v120, v64 offset:432
	ds_write_b32 v116, v65 offset:496
	s_cbranch_vccnz .LBB0_276
	v_add_f32_e32 v64, v64, v65
	v_cndmask_b32_e64 v64, -v64, v64, s[14:15]
	s_nop 1
	v_add_f32_dpp v64, v64, v64 quad_perm:[1,0,3,2] row_mask:0xf bank_mask:0xf
	s_waitcnt lgkmcnt(0)
	s_nop 1
	v_add_f32_dpp v64, v64, v64 quad_perm:[2,3,0,1] row_mask:0xf bank_mask:0xf
	s_waitcnt lgkmcnt(0)
	s_nop 1
	v_add_f32_dpp v64, v64, v64 row_half_mirror row_mask:0xf bank_mask:0xf
	s_waitcnt lgkmcnt(0)
	s_nop 1
	v_add_f32_dpp v64, v64, v64 row_mirror row_mask:0xf bank_mask:0xf
	s_and_saveexec_b64 s[4:5], s[12:13]
	s_cbranch_execz .LBB0_275
	s_waitcnt lgkmcnt(0)
	global_store_dword v[134:135], v64, off offset:204

; __device__ __forceinline__ unsigned pack2(float lo, float hi) { unsigned r; asm volatile("v_cvt_pk_bf16_f32 %0, %1, %2" : "=v"(r) : "v"(lo), "v"(hi)); return r; }
; template <int EPI>
; __device__ __forceinline__ void gemm_phase(const GemmDesc d, u16* shm, unsigned sx, unsigned srank, unsigned snloc) {
;     ...
;             for (int j = 0; j < 4; ++j) {
;               const float v0 = acc[ai][0][m][0][j] * rs0[0] + acc[ai][1][m][0][j] * rs1[0];
;               const float v1 = acc[ai][0][m][1][j] * rs0[1] + acc[ai][1][m][1][j] * rs1[1];
;               stg[(fq2 * 4 + j) * 36 + fr2] = v0; stg[(fq2 * 4 + j) * 36 + 16 + fr2] = v1;
;               if (pm == 0) {
;                 float a = (fr2 & 1) ? -(v0 + v1) : (v0 + v1);
;                 a += __shfl_xor(a, 1); a += __shfl_xor(a, 2); a += __shfl_xor(a, 4); a += __shfl_xor(a, 8);
;                 if (fr2 == 0) d.xs[((size_t)((pn & 15) * 4 + wc2)) * (NBATCH * DM) + (size_t)b * DM + z * 256 + ai * 128 + wr2 * 64 + m * 16 + fq2 * 4 + j] = a;
;               }
;             }
; #pragma unroll
;             for (int i = 0; i < 2; ++i) {
;               const int row_l = i * 8 + rl;
;               f32x4 v = *(const f32x4*)&stg[row_l * 36 + c4];
;               u32x2 w = {pack2(v[0], v[1]), pack2(v[2], v[3])};
;               *(u32x2*)(outp + (size_t)(ai * 128 + wr2 * 64 + m * 16 + row_l) * 4096) = w;
;             }
.LBB0_276:
	v_or_b32_e32 v68, 48, v132
	s_waitcnt lgkmcnt(0)
	ds_read_b128 v[64:67], v96
	s_waitcnt lgkmcnt(0)
	v_cvt_pk_bf16_f32 v64, v64, v65
	v_cvt_pk_bf16_f32 v65, v66, v67
	v_or_b32_e32 v66, v68, v114
	v_ashrrev_i32_e32 v67, 31, v66
	v_lshlrev_b64 v[66:67], 13, v[66:67]
	v_lshl_add_u64 v[66:67], v[112:113], 0, v[66:67]
	global_store_dwordx2 v[66:67], v[64:65], off
	ds_read_b128 v[64:67], v96 offset:1152
	s_waitcnt lgkmcnt(0)
	v_cvt_pk_bf16_f32 v64, v64, v65
	v_cvt_pk_bf16_f32 v65, v66, v67
	v_or_b32_e32 v66, v115, v68
	v_ashrrev_i32_e32 v67, 31, v66
	v_lshlrev_b64 v[66:67], 13, v[66:67]
	v_mul_f32_e32 v52, v52, v152
	v_mul_f32_e32 v48, v48, v151
	v_lshl_add_u64 v[66:67], v[112:113], 0, v[66:67]
	v_fmac_f32_e32 v52, v60, v136
	v_fmac_f32_e32 v48, v56, v137
	s_and_b64 vcc, exec, s[16:17]
	global_store_dwordx2 v[66:67], v[64:65], off
	ds_write_b32 v120, v52
	ds_write_b32 v116, v48 offset:64
	s_cbranch_vccnz .LBB0_280
	v_add_f32_e32 v48, v52, v48
	v_cndmask_b32_e64 v48, -v48, v48, s[14:15]
	s_nop 1
	v_add_f32_dpp v48, v48, v48 quad_perm:[1,0,3,2] row_mask:0xf bank_mask:0xf
	s_waitcnt lgkmcnt(0)
	s_nop 1
	v_add_f32_dpp v48, v48, v48 quad_perm:[2,3,0,1] row_mask:0xf bank_mask:0xf
	s_waitcnt lgkmcnt(0)
	s_nop 1
	v_add_f32_dpp v48, v48, v48 row_half_mirror row_mask:0xf bank_mask:0xf
	s_waitcnt lgkmcnt(0)
	s_nop 1
	v_add_f32_dpp v48, v48, v48 row_mirror row_mask:0xf bank_mask:0xf
	s_and_saveexec_b64 s[4:5], s[12:13]
	s_cbranch_execz .LBB0_279
	s_waitcnt lgkmcnt(0)
	global_store_dword v[134:135], v48, off offset:512

; template <int EPI>
; __device__ __forceinline__ void gemm_phase(const GemmDesc d, u16* shm, unsigned sx, unsigned srank, unsigned snloc) {
;     ...
;             for (int j = 0; j < 4; ++j) {
;               const float v0 = acc[ai][0][m][0][j] * rs0[0] + acc[ai][1][m][0][j] * rs1[0];
;               const float v1 = acc[ai][0][m][1][j] * rs0[1] + acc[ai][1][m][1][j] * rs1[1];
;               stg[(fq2 * 4 + j) * 36 + fr2] = v0; stg[(fq2 * 4 + j) * 36 + 16 + fr2] = v1;
;               if (pm == 0) {
;                 float a = (fr2 & 1) ? -(v0 + v1) : (v0 + v1);
;                 a += __shfl_xor(a, 1); a += __shfl_xor(a, 2); a += __shfl_xor(a, 4); a += __shfl_xor(a, 8);
;                 if (fr2 == 0) d.xs[((size_t)((pn & 15) * 4 + wc2)) * (NBATCH * DM) + (size_t)b * DM + z * 256 + ai * 128 + wr2 * 64 + m * 16 + fq2 * 4 + j] = a;
.LBB0_280:
	v_mul_f32_e32 v48, v53, v152
	v_mul_f32_e32 v49, v49, v151
	v_fmac_f32_e32 v48, v61, v136
	v_fmac_f32_e32 v49, v57, v137
	s_and_b64 vcc, exec, s[16:17]
	ds_write_b32 v120, v48 offset:144
	ds_write_b32 v116, v49 offset:208
	s_cbranch_vccnz .LBB0_284
	s_waitcnt lgkmcnt(2)
	v_add_f32_e32 v48, v48, v49
	v_cndmask_b32_e64 v48, -v48, v48, s[14:15]
	s_nop 1
	v_add_f32_dpp v48, v48, v48 quad_perm:[1,0,3,2] row_mask:0xf bank_mask:0xf
	s_waitcnt lgkmcnt(0)
	s_nop 1
	v_add_f32_dpp v48, v48, v48 quad_perm:[2,3,0,1] row_mask:0xf bank_mask:0xf
	s_waitcnt lgkmcnt(0)
	s_nop 1
	v_add_f32_dpp v48, v48, v48 row_half_mirror row_mask:0xf bank_mask:0xf
	s_waitcnt lgkmcnt(0)
	s_nop 1
	v_add_f32_dpp v48, v48, v48 row_mirror row_mask:0xf bank_mask:0xf
	s_and_saveexec_b64 s[4:5], s[12:13]
	s_cbranch_execz .LBB0_283
	s_waitcnt lgkmcnt(0)
	global_store_dword v[134:135], v48, off offset:516

; template <int EPI>
; __device__ __forceinline__ void gemm_phase(const GemmDesc d, u16* shm, unsigned sx, unsigned srank, unsigned snloc) {
;     ...
;             for (int j = 0; j < 4; ++j) {
;               const float v0 = acc[ai][0][m][0][j] * rs0[0] + acc[ai][1][m][0][j] * rs1[0];
;               const float v1 = acc[ai][0][m][1][j] * rs0[1] + acc[ai][1][m][1][j] * rs1[1];
;               stg[(fq2 * 4 + j) * 36 + fr2] = v0; stg[(fq2 * 4 + j) * 36 + 16 + fr2] = v1;
;               if (pm == 0) {
;                 float a = (fr2 & 1) ? -(v0 + v1) : (v0 + v1);
;                 a += __shfl_xor(a, 1); a += __shfl_xor(a, 2); a += __shfl_xor(a, 4); a += __shfl_xor(a, 8);
;                 if (fr2 == 0) d.xs[((size_t)((pn & 15) * 4 + wc2)) * (NBATCH * DM) + (size_t)b * DM + z * 256 + ai * 128 + wr2 * 64 + m * 16 + fq2 * 4 + j] = a;
.LBB0_284:
	v_mul_f32_e32 v48, v54, v152
	s_waitcnt lgkmcnt(0)
	v_mul_f32_e32 v49, v50, v151
	v_fmac_f32_e32 v48, v62, v136
	v_fmac_f32_e32 v49, v58, v137
	s_and_b64 vcc, exec, s[16:17]
	ds_write_b32 v120, v48 offset:288
	ds_write_b32 v116, v49 offset:352
	s_cbranch_vccnz .LBB0_288
	v_add_f32_e32 v48, v48, v49
	v_cndmask_b32_e64 v48, -v48, v48, s[14:15]
	s_nop 1
	v_add_f32_dpp v48, v48, v48 quad_perm:[1,0,3,2] row_mask:0xf bank_mask:0xf
	s_waitcnt lgkmcnt(0)
	s_nop 1
	v_add_f32_dpp v48, v48, v48 quad_perm:[2,3,0,1] row_mask:0xf bank_mask:0xf
	s_waitcnt lgkmcnt(0)
	s_nop 1
	v_add_f32_dpp v48, v48, v48 row_half_mirror row_mask:0xf bank_mask:0xf
	s_waitcnt lgkmcnt(0)
	s_nop 1
	v_add_f32_dpp v48, v48, v48 row_mirror row_mask:0xf bank_mask:0xf
	s_and_saveexec_b64 s[4:5], s[12:13]
	s_cbranch_execz .LBB0_287
	s_waitcnt lgkmcnt(0)
	global_store_dword v[134:135], v48, off offset:520

; template <int EPI>
; __device__ __forceinline__ void gemm_phase(const GemmDesc d, u16* shm, unsigned sx, unsigned srank, unsigned snloc) {
;     ...
;             for (int j = 0; j < 4; ++j) {
;               const float v0 = acc[ai][0][m][0][j] * rs0[0] + acc[ai][1][m][0][j] * rs1[0];
;               const float v1 = acc[ai][0][m][1][j] * rs0[1] + acc[ai][1][m][1][j] * rs1[1];
;               stg[(fq2 * 4 + j) * 36 + fr2] = v0; stg[(fq2 * 4 + j) * 36 + 16 + fr2] = v1;
;               if (pm == 0) {
;                 float a = (fr2 & 1) ? -(v0 + v1) : (v0 + v1);
;                 a += __shfl_xor(a, 1); a += __shfl_xor(a, 2); a += __shfl_xor(a, 4); a += __shfl_xor(a, 8);
;                 if (fr2 == 0) d.xs[((size_t)((pn & 15) * 4 + wc2)) * (NBATCH * DM) + (size_t)b * DM + z * 256 + ai * 128 + wr2 * 64 + m * 16 + fq2 * 4 + j] = a;
.LBB0_288:
	v_mul_f32_e32 v48, v55, v152
	s_waitcnt lgkmcnt(0)
	v_mul_f32_e32 v49, v51, v151
	v_fmac_f32_e32 v48, v63, v136
	v_fmac_f32_e32 v49, v59, v137
	s_and_b64 vcc, exec, s[16:17]
	ds_write_b32 v120, v48 offset:432
	ds_write_b32 v116, v49 offset:496
	s_cbranch_vccnz .LBB0_292
	v_add_f32_e32 v48, v48, v49
	v_cndmask_b32_e64 v48, -v48, v48, s[14:15]
	s_nop 1
	v_add_f32_dpp v48, v48, v48 quad_perm:[1,0,3,2] row_mask:0xf bank_mask:0xf
	s_waitcnt lgkmcnt(0)
	s_nop 1
	v_add_f32_dpp v48, v48, v48 quad_perm:[2,3,0,1] row_mask:0xf bank_mask:0xf
	s_waitcnt lgkmcnt(0)
	s_nop 1
	v_add_f32_dpp v48, v48, v48 row_half_mirror row_mask:0xf bank_mask:0xf
	s_waitcnt lgkmcnt(0)
	s_nop 1
	v_add_f32_dpp v48, v48, v48 row_mirror row_mask:0xf bank_mask:0xf
	s_and_saveexec_b64 s[4:5], s[12:13]
	s_cbranch_execz .LBB0_291
	s_waitcnt lgkmcnt(0)
	global_store_dword v[134:135], v48, off offset:524

; __device__ __forceinline__ unsigned pack2(float lo, float hi) { unsigned r; asm volatile("v_cvt_pk_bf16_f32 %0, %1, %2" : "=v"(r) : "v"(lo), "v"(hi)); return r; }
; template <int EPI>
; __device__ __forceinline__ void gemm_phase(const GemmDesc d, u16* shm, unsigned sx, unsigned srank, unsigned snloc) {
;     ...
;             for (int j = 0; j < 4; ++j) {
;               const float v0 = acc[ai][0][m][0][j] * rs0[0] + acc[ai][1][m][0][j] * rs1[0];
;               const float v1 = acc[ai][0][m][1][j] * rs0[1] + acc[ai][1][m][1][j] * rs1[1];
;               stg[(fq2 * 4 + j) * 36 + fr2] = v0; stg[(fq2 * 4 + j) * 36 + 16 + fr2] = v1;
;               if (pm == 0) {
;                 float a = (fr2 & 1) ? -(v0 + v1) : (v0 + v1);
;                 a += __shfl_xor(a, 1); a += __shfl_xor(a, 2); a += __shfl_xor(a, 4); a += __shfl_xor(a, 8);
;                 if (fr2 == 0) d.xs[((size_t)((pn & 15) * 4 + wc2)) * (NBATCH * DM) + (size_t)b * DM + z * 256 + ai * 128 + wr2 * 64 + m * 16 + fq2 * 4 + j] = a;
;               }
;             }
; #pragma unroll
;             for (int i = 0; i < 2; ++i) {
;               const int row_l = i * 8 + rl;
;               f32x4 v = *(const f32x4*)&stg[row_l * 36 + c4];
;               u32x2 w = {pack2(v[0], v[1]), pack2(v[2], v[3])};
;               *(u32x2*)(outp + (size_t)(ai * 128 + wr2 * 64 + m * 16 + row_l) * 4096) = w;
;             }
.LBB0_292:
	v_add_u32_e32 v52, 0x80, v132
	s_waitcnt lgkmcnt(0)
	ds_read_b128 v[48:51], v96
	s_waitcnt lgkmcnt(0)
	v_cvt_pk_bf16_f32 v48, v48, v49
	v_cvt_pk_bf16_f32 v49, v50, v51
	v_or_b32_e32 v50, v52, v114
	v_ashrrev_i32_e32 v51, 31, v50
	v_lshlrev_b64 v[50:51], 13, v[50:51]
	v_lshl_add_u64 v[50:51], v[112:113], 0, v[50:51]
	global_store_dwordx2 v[50:51], v[48:49], off
	ds_read_b128 v[48:51], v96 offset:1152
	s_waitcnt lgkmcnt(0)
	v_cvt_pk_bf16_f32 v48, v48, v49
	v_cvt_pk_bf16_f32 v49, v50, v51
	v_or_b32_e32 v50, v115, v52
	v_ashrrev_i32_e32 v51, 31, v50
	v_lshlrev_b64 v[50:51], 13, v[50:51]
	v_mul_f32_e32 v36, v36, v152
	v_mul_f32_e32 v32, v32, v151
	v_lshl_add_u64 v[50:51], v[112:113], 0, v[50:51]
	v_fmac_f32_e32 v36, v44, v136
	v_fmac_f32_e32 v32, v40, v137
	s_and_b64 vcc, exec, s[16:17]
	global_store_dwordx2 v[50:51], v[48:49], off
	ds_write_b32 v120, v36
	ds_write_b32 v116, v32 offset:64
	s_cbranch_vccnz .LBB0_296
	v_add_f32_e32 v32, v36, v32
	v_cndmask_b32_e64 v32, -v32, v32, s[14:15]
	s_nop 1
	v_add_f32_dpp v32, v32, v32 quad_perm:[1,0,3,2] row_mask:0xf bank_mask:0xf
	s_waitcnt lgkmcnt(0)
	s_nop 1
	v_add_f32_dpp v32, v32, v32 quad_perm:[2,3,0,1] row_mask:0xf bank_mask:0xf
	s_waitcnt lgkmcnt(0)
	s_nop 1
	v_add_f32_dpp v32, v32, v32 row_half_mirror row_mask:0xf bank_mask:0xf
	s_waitcnt lgkmcnt(0)
	s_nop 1
	v_add_f32_dpp v32, v32, v32 row_mirror row_mask:0xf bank_mask:0xf
	s_and_saveexec_b64 s[4:5], s[12:13]
	s_cbranch_execz .LBB0_295
	s_waitcnt lgkmcnt(0)
	global_store_dword v[134:135], v32, off offset:576

; template <int EPI>
; __device__ __forceinline__ void gemm_phase(const GemmDesc d, u16* shm, unsigned sx, unsigned srank, unsigned snloc) {
;     ...
;             for (int j = 0; j < 4; ++j) {
;               const float v0 = acc[ai][0][m][0][j] * rs0[0] + acc[ai][1][m][0][j] * rs1[0];
;               const float v1 = acc[ai][0][m][1][j] * rs0[1] + acc[ai][1][m][1][j] * rs1[1];
;               stg[(fq2 * 4 + j) * 36 + fr2] = v0; stg[(fq2 * 4 + j) * 36 + 16 + fr2] = v1;
;               if (pm == 0) {
;                 float a = (fr2 & 1) ? -(v0 + v1) : (v0 + v1);
;                 a += __shfl_xor(a, 1); a += __shfl_xor(a, 2); a += __shfl_xor(a, 4); a += __shfl_xor(a, 8);
;                 if (fr2 == 0) d.xs[((size_t)((pn & 15) * 4 + wc2)) * (NBATCH * DM) + (size_t)b * DM + z * 256 + ai * 128 + wr2 * 64 + m * 16 + fq2 * 4 + j] = a;
.LBB0_296:
	v_mul_f32_e32 v32, v37, v152
	v_mul_f32_e32 v33, v33, v151
	v_fmac_f32_e32 v32, v45, v136
	v_fmac_f32_e32 v33, v41, v137
	s_and_b64 vcc, exec, s[16:17]
	ds_write_b32 v120, v32 offset:144
	ds_write_b32 v116, v33 offset:208
	s_cbranch_vccnz .LBB0_300
	s_waitcnt lgkmcnt(2)
	v_add_f32_e32 v32, v32, v33
	v_cndmask_b32_e64 v32, -v32, v32, s[14:15]
	s_nop 1
	v_add_f32_dpp v32, v32, v32 quad_perm:[1,0,3,2] row_mask:0xf bank_mask:0xf
	s_waitcnt lgkmcnt(0)
	s_nop 1
	v_add_f32_dpp v32, v32, v32 quad_perm:[2,3,0,1] row_mask:0xf bank_mask:0xf
	s_waitcnt lgkmcnt(0)
	s_nop 1
	v_add_f32_dpp v32, v32, v32 row_half_mirror row_mask:0xf bank_mask:0xf
	s_waitcnt lgkmcnt(0)
	s_nop 1
	v_add_f32_dpp v32, v32, v32 row_mirror row_mask:0xf bank_mask:0xf
	s_and_saveexec_b64 s[4:5], s[12:13]
	s_cbranch_execz .LBB0_299
	s_waitcnt lgkmcnt(0)
	global_store_dword v[134:135], v32, off offset:580

; template <int EPI>
; __device__ __forceinline__ void gemm_phase(const GemmDesc d, u16* shm, unsigned sx, unsigned srank, unsigned snloc) {
;     ...
;             for (int j = 0; j < 4; ++j) {
;               const float v0 = acc[ai][0][m][0][j] * rs0[0] + acc[ai][1][m][0][j] * rs1[0];
;               const float v1 = acc[ai][0][m][1][j] * rs0[1] + acc[ai][1][m][1][j] * rs1[1];
;               stg[(fq2 * 4 + j) * 36 + fr2] = v0; stg[(fq2 * 4 + j) * 36 + 16 + fr2] = v1;
;               if (pm == 0) {
;                 float a = (fr2 & 1) ? -(v0 + v1) : (v0 + v1);
;                 a += __shfl_xor(a, 1); a += __shfl_xor(a, 2); a += __shfl_xor(a, 4); a += __shfl_xor(a, 8);
;                 if (fr2 == 0) d.xs[((size_t)((pn & 15) * 4 + wc2)) * (NBATCH * DM) + (size_t)b * DM + z * 256 + ai * 128 + wr2 * 64 + m * 16 + fq2 * 4 + j] = a;
.LBB0_300:
	v_mul_f32_e32 v32, v38, v152
	s_waitcnt lgkmcnt(0)
	v_mul_f32_e32 v33, v34, v151
	v_fmac_f32_e32 v32, v46, v136
	v_fmac_f32_e32 v33, v42, v137
	s_and_b64 vcc, exec, s[16:17]
	ds_write_b32 v120, v32 offset:288
	ds_write_b32 v116, v33 offset:352
	s_cbranch_vccnz .LBB0_304
	v_add_f32_e32 v32, v32, v33
	v_cndmask_b32_e64 v32, -v32, v32, s[14:15]
	s_nop 1
	v_add_f32_dpp v32, v32, v32 quad_perm:[1,0,3,2] row_mask:0xf bank_mask:0xf
	s_waitcnt lgkmcnt(0)
	s_nop 1
	v_add_f32_dpp v32, v32, v32 quad_perm:[2,3,0,1] row_mask:0xf bank_mask:0xf
	s_waitcnt lgkmcnt(0)
	s_nop 1
	v_add_f32_dpp v32, v32, v32 row_half_mirror row_mask:0xf bank_mask:0xf
	s_waitcnt lgkmcnt(0)
	s_nop 1
	v_add_f32_dpp v32, v32, v32 row_mirror row_mask:0xf bank_mask:0xf
	s_and_saveexec_b64 s[4:5], s[12:13]
	s_cbranch_execz .LBB0_303
	s_waitcnt lgkmcnt(0)
	global_store_dword v[134:135], v32, off offset:584

; template <int EPI>
; __device__ __forceinline__ void gemm_phase(const GemmDesc d, u16* shm, unsigned sx, unsigned srank, unsigned snloc) {
;     ...
;             for (int j = 0; j < 4; ++j) {
;               const float v0 = acc[ai][0][m][0][j] * rs0[0] + acc[ai][1][m][0][j] * rs1[0];
;               const float v1 = acc[ai][0][m][1][j] * rs0[1] + acc[ai][1][m][1][j] * rs1[1];
;               stg[(fq2 * 4 + j) * 36 + fr2] = v0; stg[(fq2 * 4 + j) * 36 + 16 + fr2] = v1;
;               if (pm == 0) {
;                 float a = (fr2 & 1) ? -(v0 + v1) : (v0 + v1);
;                 a += __shfl_xor(a, 1); a += __shfl_xor(a, 2); a += __shfl_xor(a, 4); a += __shfl_xor(a, 8);
;                 if (fr2 == 0) d.xs[((size_t)((pn & 15) * 4 + wc2)) * (NBATCH * DM) + (size_t)b * DM + z * 256 + ai * 128 + wr2 * 64 + m * 16 + fq2 * 4 + j] = a;
.LBB0_304:
	v_mul_f32_e32 v32, v39, v152
	s_waitcnt lgkmcnt(0)
	v_mul_f32_e32 v33, v35, v151
	v_fmac_f32_e32 v32, v47, v136
	v_fmac_f32_e32 v33, v43, v137
	s_and_b64 vcc, exec, s[16:17]
	ds_write_b32 v120, v32 offset:432
	ds_write_b32 v116, v33 offset:496
	s_cbranch_vccnz .LBB0_308
	v_add_f32_e32 v32, v32, v33
	v_cndmask_b32_e64 v32, -v32, v32, s[14:15]
	s_nop 1
	v_add_f32_dpp v32, v32, v32 quad_perm:[1,0,3,2] row_mask:0xf bank_mask:0xf
	s_waitcnt lgkmcnt(0)
	s_nop 1
	v_add_f32_dpp v32, v32, v32 quad_perm:[2,3,0,1] row_mask:0xf bank_mask:0xf
	s_waitcnt lgkmcnt(0)
	s_nop 1
	v_add_f32_dpp v32, v32, v32 row_half_mirror row_mask:0xf bank_mask:0xf
	s_waitcnt lgkmcnt(0)
	s_nop 1
	v_add_f32_dpp v32, v32, v32 row_mirror row_mask:0xf bank_mask:0xf
	s_and_saveexec_b64 s[4:5], s[12:13]
	s_cbranch_execz .LBB0_307
	s_waitcnt lgkmcnt(0)
	global_store_dword v[134:135], v32, off offset:588

; __device__ __forceinline__ unsigned pack2(float lo, float hi) { unsigned r; asm volatile("v_cvt_pk_bf16_f32 %0, %1, %2" : "=v"(r) : "v"(lo), "v"(hi)); return r; }
; template <int EPI>
; __device__ __forceinline__ void gemm_phase(const GemmDesc d, u16* shm, unsigned sx, unsigned srank, unsigned snloc) {
;     ...
;             for (int j = 0; j < 4; ++j) {
;               const float v0 = acc[ai][0][m][0][j] * rs0[0] + acc[ai][1][m][0][j] * rs1[0];
;               const float v1 = acc[ai][0][m][1][j] * rs0[1] + acc[ai][1][m][1][j] * rs1[1];
;               stg[(fq2 * 4 + j) * 36 + fr2] = v0; stg[(fq2 * 4 + j) * 36 + 16 + fr2] = v1;
;               if (pm == 0) {
;                 float a = (fr2 & 1) ? -(v0 + v1) : (v0 + v1);
;                 a += __shfl_xor(a, 1); a += __shfl_xor(a, 2); a += __shfl_xor(a, 4); a += __shfl_xor(a, 8);
;                 if (fr2 == 0) d.xs[((size_t)((pn & 15) * 4 + wc2)) * (NBATCH * DM) + (size_t)b * DM + z * 256 + ai * 128 + wr2 * 64 + m * 16 + fq2 * 4 + j] = a;
;               }
;             }
; #pragma unroll
;             for (int i = 0; i < 2; ++i) {
;               const int row_l = i * 8 + rl;
;               f32x4 v = *(const f32x4*)&stg[row_l * 36 + c4];
;               u32x2 w = {pack2(v[0], v[1]), pack2(v[2], v[3])};
;               *(u32x2*)(outp + (size_t)(ai * 128 + wr2 * 64 + m * 16 + row_l) * 4096) = w;
;             }
.LBB0_308:
	v_add_u32_e32 v36, 0x90, v132
	s_waitcnt lgkmcnt(0)
	ds_read_b128 v[32:35], v96
	s_waitcnt lgkmcnt(0)
	v_cvt_pk_bf16_f32 v32, v32, v33
	v_cvt_pk_bf16_f32 v33, v34, v35
	v_or_b32_e32 v34, v36, v114
	v_ashrrev_i32_e32 v35, 31, v34
	v_lshlrev_b64 v[34:35], 13, v[34:35]
	v_lshl_add_u64 v[34:35], v[112:113], 0, v[34:35]
	global_store_dwordx2 v[34:35], v[32:33], off
	ds_read_b128 v[32:35], v96 offset:1152
	s_waitcnt lgkmcnt(0)
	v_cvt_pk_bf16_f32 v32, v32, v33
	v_cvt_pk_bf16_f32 v33, v34, v35
	v_or_b32_e32 v34, v115, v36
	v_ashrrev_i32_e32 v35, 31, v34
	v_mul_f32_e32 v24, v24, v152
	v_lshlrev_b64 v[34:35], 13, v[34:35]
	v_fmac_f32_e32 v24, v20, v136
	v_mul_f32_e32 v20, v28, v151
	v_lshl_add_u64 v[34:35], v[112:113], 0, v[34:35]
	v_fmac_f32_e32 v20, v16, v137
	s_and_b64 vcc, exec, s[16:17]
	global_store_dwordx2 v[34:35], v[32:33], off
	ds_write_b32 v120, v24
	ds_write_b32 v116, v20 offset:64
	s_cbranch_vccnz .LBB0_312
	v_add_f32_e32 v16, v24, v20
	v_cndmask_b32_e64 v16, -v16, v16, s[14:15]
	s_nop 1
	v_add_f32_dpp v16, v16, v16 quad_perm:[1,0,3,2] row_mask:0xf bank_mask:0xf
	s_waitcnt lgkmcnt(0)
	s_nop 1
	v_add_f32_dpp v16, v16, v16 quad_perm:[2,3,0,1] row_mask:0xf bank_mask:0xf
	s_waitcnt lgkmcnt(0)
	s_nop 1
	v_add_f32_dpp v16, v16, v16 row_half_mirror row_mask:0xf bank_mask:0xf
	s_waitcnt lgkmcnt(0)
	s_nop 1
	v_add_f32_dpp v16, v16, v16 row_mirror row_mask:0xf bank_mask:0xf
	s_and_saveexec_b64 s[4:5], s[12:13]
	s_cbranch_execz .LBB0_311
	s_waitcnt lgkmcnt(0)
	global_store_dword v[134:135], v16, off offset:640

; template <int EPI>
; __device__ __forceinline__ void gemm_phase(const GemmDesc d, u16* shm, unsigned sx, unsigned srank, unsigned snloc) {
;     ...
;             for (int j = 0; j < 4; ++j) {
;               const float v0 = acc[ai][0][m][0][j] * rs0[0] + acc[ai][1][m][0][j] * rs1[0];
;               const float v1 = acc[ai][0][m][1][j] * rs0[1] + acc[ai][1][m][1][j] * rs1[1];
;               stg[(fq2 * 4 + j) * 36 + fr2] = v0; stg[(fq2 * 4 + j) * 36 + 16 + fr2] = v1;
;               if (pm == 0) {
;                 float a = (fr2 & 1) ? -(v0 + v1) : (v0 + v1);
;                 a += __shfl_xor(a, 1); a += __shfl_xor(a, 2); a += __shfl_xor(a, 4); a += __shfl_xor(a, 8);
;                 if (fr2 == 0) d.xs[((size_t)((pn & 15) * 4 + wc2)) * (NBATCH * DM) + (size_t)b * DM + z * 256 + ai * 128 + wr2 * 64 + m * 16 + fq2 * 4 + j] = a;
.LBB0_312:
	v_mul_f32_e32 v16, v25, v152
	s_waitcnt lgkmcnt(0)
	v_mul_f32_e32 v20, v29, v151
	v_fmac_f32_e32 v16, v21, v136
	v_fmac_f32_e32 v20, v17, v137
	s_and_b64 vcc, exec, s[16:17]
	ds_write_b32 v120, v16 offset:144
	ds_write_b32 v116, v20 offset:208
	s_cbranch_vccnz .LBB0_316
	v_add_f32_e32 v16, v16, v20
	v_cndmask_b32_e64 v16, -v16, v16, s[14:15]
	s_nop 1
	v_add_f32_dpp v16, v16, v16 quad_perm:[1,0,3,2] row_mask:0xf bank_mask:0xf
	s_waitcnt lgkmcnt(0)
	s_nop 1
	v_add_f32_dpp v16, v16, v16 quad_perm:[2,3,0,1] row_mask:0xf bank_mask:0xf
	s_waitcnt lgkmcnt(0)
	s_nop 1
	v_add_f32_dpp v16, v16, v16 row_half_mirror row_mask:0xf bank_mask:0xf
	s_waitcnt lgkmcnt(0)
	s_nop 1
	v_add_f32_dpp v16, v16, v16 row_mirror row_mask:0xf bank_mask:0xf
	s_and_saveexec_b64 s[4:5], s[12:13]
	s_cbranch_execz .LBB0_315
	s_waitcnt lgkmcnt(0)
	global_store_dword v[134:135], v16, off offset:644

; template <int EPI>
; __device__ __forceinline__ void gemm_phase(const GemmDesc d, u16* shm, unsigned sx, unsigned srank, unsigned snloc) {
;     ...
;             for (int j = 0; j < 4; ++j) {
;               const float v0 = acc[ai][0][m][0][j] * rs0[0] + acc[ai][1][m][0][j] * rs1[0];
;               const float v1 = acc[ai][0][m][1][j] * rs0[1] + acc[ai][1][m][1][j] * rs1[1];
;               stg[(fq2 * 4 + j) * 36 + fr2] = v0; stg[(fq2 * 4 + j) * 36 + 16 + fr2] = v1;
;               if (pm == 0) {
;                 float a = (fr2 & 1) ? -(v0 + v1) : (v0 + v1);
;                 a += __shfl_xor(a, 1); a += __shfl_xor(a, 2); a += __shfl_xor(a, 4); a += __shfl_xor(a, 8);
;                 if (fr2 == 0) d.xs[((size_t)((pn & 15) * 4 + wc2)) * (NBATCH * DM) + (size_t)b * DM + z * 256 + ai * 128 + wr2 * 64 + m * 16 + fq2 * 4 + j] = a;
.LBB0_316:
	v_mul_f32_e32 v16, v26, v152
	s_waitcnt lgkmcnt(0)
	v_mul_f32_e32 v17, v30, v151
	v_fmac_f32_e32 v16, v22, v136
	v_fmac_f32_e32 v17, v18, v137
	s_and_b64 vcc, exec, s[16:17]
	ds_write_b32 v120, v16 offset:288
	ds_write_b32 v116, v17 offset:352
	s_cbranch_vccnz .LBB0_320
	v_add_f32_e32 v16, v16, v17
	v_cndmask_b32_e64 v16, -v16, v16, s[14:15]
	s_nop 1
	v_add_f32_dpp v16, v16, v16 quad_perm:[1,0,3,2] row_mask:0xf bank_mask:0xf
	s_waitcnt lgkmcnt(0)
	s_nop 1
	v_add_f32_dpp v16, v16, v16 quad_perm:[2,3,0,1] row_mask:0xf bank_mask:0xf
	s_waitcnt lgkmcnt(0)
	s_nop 1
	v_add_f32_dpp v16, v16, v16 row_half_mirror row_mask:0xf bank_mask:0xf
	s_waitcnt lgkmcnt(0)
	s_nop 1
	v_add_f32_dpp v16, v16, v16 row_mirror row_mask:0xf bank_mask:0xf
	s_and_saveexec_b64 s[4:5], s[12:13]
	s_cbranch_execz .LBB0_319
	s_waitcnt lgkmcnt(0)
	global_store_dword v[134:135], v16, off offset:648

; template <int EPI>
; __device__ __forceinline__ void gemm_phase(const GemmDesc d, u16* shm, unsigned sx, unsigned srank, unsigned snloc) {
;     ...
;               const float v0 = acc[ai][0][m][0][j] * rs0[0] + acc[ai][1][m][0][j] * rs1[0];
;               const float v1 = acc[ai][0][m][1][j] * rs0[1] + acc[ai][1][m][1][j] * rs1[1];
;               stg[(fq2 * 4 + j) * 36 + fr2] = v0; stg[(fq2 * 4 + j) * 36 + 16 + fr2] = v1;
;               if (pm == 0) {
;                 float a = (fr2 & 1) ? -(v0 + v1) : (v0 + v1);
;                 a += __shfl_xor(a, 1); a += __shfl_xor(a, 2); a += __shfl_xor(a, 4); a += __shfl_xor(a, 8);
;                 if (fr2 == 0) d.xs[((size_t)((pn & 15) * 4 + wc2)) * (NBATCH * DM) + (size_t)b * DM + z * 256 + ai * 128 + wr2 * 64 + m * 16 + fq2 * 4 + j] = a;
.LBB0_320:
	v_mul_f32_e32 v16, v27, v152
	s_waitcnt lgkmcnt(0)
	v_mul_f32_e32 v17, v31, v151
	v_fmac_f32_e32 v16, v23, v136
	v_fmac_f32_e32 v17, v19, v137
	s_and_b64 vcc, exec, s[16:17]
	ds_write_b32 v120, v16 offset:432
	ds_write_b32 v116, v17 offset:496
	s_cbranch_vccnz .LBB0_324
	v_add_f32_e32 v16, v16, v17
	v_cndmask_b32_e64 v16, -v16, v16, s[14:15]
	s_nop 1
	v_add_f32_dpp v16, v16, v16 quad_perm:[1,0,3,2] row_mask:0xf bank_mask:0xf
	s_waitcnt lgkmcnt(0)
	s_nop 1
	v_add_f32_dpp v16, v16, v16 quad_perm:[2,3,0,1] row_mask:0xf bank_mask:0xf
	s_waitcnt lgkmcnt(0)
	s_nop 1
	v_add_f32_dpp v16, v16, v16 row_half_mirror row_mask:0xf bank_mask:0xf
	s_waitcnt lgkmcnt(0)
	s_nop 1
	v_add_f32_dpp v16, v16, v16 row_mirror row_mask:0xf bank_mask:0xf
	s_and_saveexec_b64 s[4:5], s[12:13]
	s_cbranch_execz .LBB0_323
	s_waitcnt lgkmcnt(0)
	global_store_dword v[134:135], v16, off offset:652

; __device__ __forceinline__ unsigned pack2(float lo, float hi) { unsigned r; asm volatile("v_cvt_pk_bf16_f32 %0, %1, %2" : "=v"(r) : "v"(lo), "v"(hi)); return r; }
; template <int EPI>
; __device__ __forceinline__ void gemm_phase(const GemmDesc d, u16* shm, unsigned sx, unsigned srank, unsigned snloc) {
;     ...
;               const float v0 = acc[ai][0][m][0][j] * rs0[0] + acc[ai][1][m][0][j] * rs1[0];
;               const float v1 = acc[ai][0][m][1][j] * rs0[1] + acc[ai][1][m][1][j] * rs1[1];
;               stg[(fq2 * 4 + j) * 36 + fr2] = v0; stg[(fq2 * 4 + j) * 36 + 16 + fr2] = v1;
;               if (pm == 0) {
;                 float a = (fr2 & 1) ? -(v0 + v1) : (v0 + v1);
;                 a += __shfl_xor(a, 1); a += __shfl_xor(a, 2); a += __shfl_xor(a, 4); a += __shfl_xor(a, 8);
;                 if (fr2 == 0) d.xs[((size_t)((pn & 15) * 4 + wc2)) * (NBATCH * DM) + (size_t)b * DM + z * 256 + ai * 128 + wr2 * 64 + m * 16 + fq2 * 4 + j] = a;
;               }
;             }
; #pragma unroll
;             for (int i = 0; i < 2; ++i) {
;               const int row_l = i * 8 + rl;
;               f32x4 v = *(const f32x4*)&stg[row_l * 36 + c4];
;               u32x2 w = {pack2(v[0], v[1]), pack2(v[2], v[3])};
;               *(u32x2*)(outp + (size_t)(ai * 128 + wr2 * 64 + m * 16 + row_l) * 4096) = w;
.LBB0_324:
	v_add_u32_e32 v20, 0xa0, v132
	s_waitcnt lgkmcnt(0)
	ds_read_b128 v[16:19], v96
	s_waitcnt lgkmcnt(0)
	v_cvt_pk_bf16_f32 v16, v16, v17
	v_cvt_pk_bf16_f32 v17, v18, v19
	v_or_b32_e32 v18, v20, v114
	v_ashrrev_i32_e32 v19, 31, v18
	v_lshlrev_b64 v[18:19], 13, v[18:19]
	v_lshl_add_u64 v[18:19], v[112:113], 0, v[18:19]
	global_store_dwordx2 v[18:19], v[16:17], off
	ds_read_b128 v[16:19], v96 offset:1152
	s_waitcnt lgkmcnt(0)
	v_cvt_pk_bf16_f32 v16, v16, v17
	v_cvt_pk_bf16_f32 v17, v18, v19
	v_or_b32_e32 v18, v115, v20
	v_ashrrev_i32_e32 v19, 31, v18
	v_mul_f32_e32 v8, v8, v152
	v_lshlrev_b64 v[18:19], 13, v[18:19]
	v_fmac_f32_e32 v8, v4, v136
	v_mul_f32_e32 v4, v12, v151
	v_lshl_add_u64 v[18:19], v[112:113], 0, v[18:19]
	v_fmac_f32_e32 v4, v0, v137
	s_and_b64 vcc, exec, s[16:17]
	global_store_dwordx2 v[18:19], v[16:17], off
	ds_write_b32 v120, v8
	ds_write_b32 v116, v4 offset:64
	s_cbranch_vccnz .LBB0_328
	v_add_f32_e32 v0, v8, v4
	v_cndmask_b32_e64 v0, -v0, v0, s[14:15]
	s_nop 1
	v_add_f32_dpp v0, v0, v0 quad_perm:[1,0,3,2] row_mask:0xf bank_mask:0xf
	s_waitcnt lgkmcnt(0)
	s_nop 1
	v_add_f32_dpp v0, v0, v0 quad_perm:[2,3,0,1] row_mask:0xf bank_mask:0xf
	s_waitcnt lgkmcnt(0)
	s_nop 1
	v_add_f32_dpp v0, v0, v0 row_half_mirror row_mask:0xf bank_mask:0xf
	s_waitcnt lgkmcnt(0)
	s_nop 1
	v_add_f32_dpp v0, v0, v0 row_mirror row_mask:0xf bank_mask:0xf
	s_and_saveexec_b64 s[4:5], s[12:13]
	s_cbranch_execz .LBB0_327
	s_waitcnt lgkmcnt(0)
	global_store_dword v[134:135], v0, off offset:704

; template <int EPI>
; __device__ __forceinline__ void gemm_phase(const GemmDesc d, u16* shm, unsigned sx, unsigned srank, unsigned snloc) {
;     ...
;               const float v0 = acc[ai][0][m][0][j] * rs0[0] + acc[ai][1][m][0][j] * rs1[0];
;               const float v1 = acc[ai][0][m][1][j] * rs0[1] + acc[ai][1][m][1][j] * rs1[1];
;               stg[(fq2 * 4 + j) * 36 + fr2] = v0; stg[(fq2 * 4 + j) * 36 + 16 + fr2] = v1;
;               if (pm == 0) {
;                 float a = (fr2 & 1) ? -(v0 + v1) : (v0 + v1);
;                 a += __shfl_xor(a, 1); a += __shfl_xor(a, 2); a += __shfl_xor(a, 4); a += __shfl_xor(a, 8);
;                 if (fr2 == 0) d.xs[((size_t)((pn & 15) * 4 + wc2)) * (NBATCH * DM) + (size_t)b * DM + z * 256 + ai * 128 + wr2 * 64 + m * 16 + fq2 * 4 + j] = a;
.LBB0_328:
	v_mul_f32_e32 v0, v9, v152
	s_waitcnt lgkmcnt(0)
	v_mul_f32_e32 v4, v13, v151
	v_fmac_f32_e32 v0, v5, v136
	v_fmac_f32_e32 v4, v1, v137
	s_and_b64 vcc, exec, s[16:17]
	ds_write_b32 v120, v0 offset:144
	ds_write_b32 v116, v4 offset:208
	s_cbranch_vccnz .LBB0_332
	v_add_f32_e32 v0, v0, v4
	v_cndmask_b32_e64 v0, -v0, v0, s[14:15]
	s_nop 1
	v_add_f32_dpp v0, v0, v0 quad_perm:[1,0,3,2] row_mask:0xf bank_mask:0xf
	s_waitcnt lgkmcnt(0)
	s_nop 1
	v_add_f32_dpp v0, v0, v0 quad_perm:[2,3,0,1] row_mask:0xf bank_mask:0xf
	s_waitcnt lgkmcnt(0)
	s_nop 1
	v_add_f32_dpp v0, v0, v0 row_half_mirror row_mask:0xf bank_mask:0xf
	s_waitcnt lgkmcnt(0)
	s_nop 1
	v_add_f32_dpp v0, v0, v0 row_mirror row_mask:0xf bank_mask:0xf
	s_and_saveexec_b64 s[4:5], s[12:13]
	s_cbranch_execz .LBB0_331
	s_waitcnt lgkmcnt(0)
	global_store_dword v[134:135], v0, off offset:708

; template <int EPI>
; __device__ __forceinline__ void gemm_phase(const GemmDesc d, u16* shm, unsigned sx, unsigned srank, unsigned snloc) {
;     ...
;               const float v0 = acc[ai][0][m][0][j] * rs0[0] + acc[ai][1][m][0][j] * rs1[0];
;               const float v1 = acc[ai][0][m][1][j] * rs0[1] + acc[ai][1][m][1][j] * rs1[1];
;               stg[(fq2 * 4 + j) * 36 + fr2] = v0; stg[(fq2 * 4 + j) * 36 + 16 + fr2] = v1;
;               if (pm == 0) {
;                 float a = (fr2 & 1) ? -(v0 + v1) : (v0 + v1);
;                 a += __shfl_xor(a, 1); a += __shfl_xor(a, 2); a += __shfl_xor(a, 4); a += __shfl_xor(a, 8);
;                 if (fr2 == 0) d.xs[((size_t)((pn & 15) * 4 + wc2)) * (NBATCH * DM) + (size_t)b * DM + z * 256 + ai * 128 + wr2 * 64 + m * 16 + fq2 * 4 + j] = a;
.LBB0_332:
	v_mul_f32_e32 v0, v10, v152
	s_waitcnt lgkmcnt(0)
	v_mul_f32_e32 v1, v14, v151
	v_fmac_f32_e32 v0, v6, v136
	v_fmac_f32_e32 v1, v2, v137
	s_and_b64 vcc, exec, s[16:17]
	ds_write_b32 v120, v0 offset:288
	ds_write_b32 v116, v1 offset:352
	s_cbranch_vccnz .LBB0_336
	v_add_f32_e32 v0, v0, v1
	v_cndmask_b32_e64 v0, -v0, v0, s[14:15]
	s_nop 1
	v_add_f32_dpp v0, v0, v0 quad_perm:[1,0,3,2] row_mask:0xf bank_mask:0xf
	s_waitcnt lgkmcnt(0)
	s_nop 1
	v_add_f32_dpp v0, v0, v0 quad_perm:[2,3,0,1] row_mask:0xf bank_mask:0xf
	s_waitcnt lgkmcnt(0)
	s_nop 1
	v_add_f32_dpp v0, v0, v0 row_half_mirror row_mask:0xf bank_mask:0xf
	s_waitcnt lgkmcnt(0)
	s_nop 1
	v_add_f32_dpp v0, v0, v0 row_mirror row_mask:0xf bank_mask:0xf
	s_and_saveexec_b64 s[4:5], s[12:13]
	s_cbranch_execz .LBB0_335
	s_waitcnt lgkmcnt(0)
	global_store_dword v[134:135], v0, off offset:712

; template <int EPI>
; __device__ __forceinline__ void gemm_phase(const GemmDesc d, u16* shm, unsigned sx, unsigned srank, unsigned snloc) {
;     ...
;               const float v0 = acc[ai][0][m][0][j] * rs0[0] + acc[ai][1][m][0][j] * rs1[0];
;               const float v1 = acc[ai][0][m][1][j] * rs0[1] + acc[ai][1][m][1][j] * rs1[1];
;               stg[(fq2 * 4 + j) * 36 + fr2] = v0; stg[(fq2 * 4 + j) * 36 + 16 + fr2] = v1;
;               if (pm == 0) {
;                 float a = (fr2 & 1) ? -(v0 + v1) : (v0 + v1);
;                 a += __shfl_xor(a, 1); a += __shfl_xor(a, 2); a += __shfl_xor(a, 4); a += __shfl_xor(a, 8);
;                 if (fr2 == 0) d.xs[((size_t)((pn & 15) * 4 + wc2)) * (NBATCH * DM) + (size_t)b * DM + z * 256 + ai * 128 + wr2 * 64 + m * 16 + fq2 * 4 + j] = a;
.LBB0_336:
	v_mul_f32_e32 v0, v11, v152
	s_waitcnt lgkmcnt(0)
	v_mul_f32_e32 v1, v15, v151
	v_fmac_f32_e32 v0, v7, v136
	v_fmac_f32_e32 v1, v3, v137
	s_and_b64 vcc, exec, s[16:17]
	ds_write_b32 v120, v0 offset:432
	ds_write_b32 v116, v1 offset:496
	s_cbranch_vccnz .LBB0_340
	v_add_f32_e32 v0, v0, v1
	v_cndmask_b32_e64 v0, -v0, v0, s[14:15]
	s_nop 1
	v_add_f32_dpp v0, v0, v0 quad_perm:[1,0,3,2] row_mask:0xf bank_mask:0xf
	s_waitcnt lgkmcnt(0)
	s_nop 1
	v_add_f32_dpp v0, v0, v0 quad_perm:[2,3,0,1] row_mask:0xf bank_mask:0xf
	s_waitcnt lgkmcnt(0)
	s_nop 1
	v_add_f32_dpp v0, v0, v0 row_half_mirror row_mask:0xf bank_mask:0xf
	s_waitcnt lgkmcnt(0)
	s_nop 1
	v_add_f32_dpp v0, v0, v0 row_mirror row_mask:0xf bank_mask:0xf
	s_and_saveexec_b64 s[4:5], s[12:13]
	s_cbranch_execz .LBB0_339
	s_waitcnt lgkmcnt(0)
	global_store_dword v[134:135], v0, off offset:716
